# att17 = att14 + next-unit prefetch (7.10): next attention unit-map's K0/K1/K2 tiles DMA'd into the dead K ring at the final step, prologue skips them
# speedup vs baseline: 1.0033x; 1.0032x over previous
.LBB0_278:
	v_and_b32_e32 v0, 63, v244
	v_lshlrev_b32_e32 v0, 2, v0
	global_load_dword v2, v0, s[72:73]
	global_load_dword v3, v0, s[74:75]
	global_load_dword v4, v0, s[76:77]
	s_nop 0
	global_load_dword v0, v0, s[78:79]
	v_mbcnt_hi_u32_b32 v5, -1, v145
	v_and_b32_e32 v6, 64, v5
	v_xor_b32_e32 v7, 1, v5
	v_add_u32_e32 v6, 64, v6
	v_cmp_lt_i32_e32 vcc, v7, v6
	v_xor_b32_e32 v8, 2, v5
	v_xor_b32_e32 v9, 4, v5
	v_cndmask_b32_e32 v7, v5, v7, vcc
	v_lshlrev_b32_e32 v232, 2, v7
	v_cmp_lt_i32_e32 vcc, v8, v6
	v_xor_b32_e32 v10, 8, v5
	v_xor_b32_e32 v11, 16, v5
	v_cndmask_b32_e32 v8, v5, v8, vcc
	v_lshlrev_b32_e32 v8, 2, v8
	v_cmp_lt_i32_e32 vcc, v9, v6
	v_xor_b32_e32 v12, 32, v5
	s_add_u32 s94, s22, 0xb000000
	v_cndmask_b32_e32 v9, v5, v9, vcc
	v_cmp_lt_i32_e32 vcc, v10, v6
	s_addc_u32 s95, s23, 0
	s_add_u32 s0, s22, 0xf000000
	v_cndmask_b32_e32 v10, v5, v10, vcc
	v_cmp_lt_i32_e32 vcc, v11, v6
	s_addc_u32 s1, s23, 0
	v_writelane_b32 v254, s0, 35
	s_mov_b32 s7, 0
	v_mov_b32_e32 v1, 0
	v_writelane_b32 v254, s1, 36
	s_add_u32 s0, s22, 0x13000000
	s_addc_u32 s1, s23, 0
	s_add_u32 s86, s20, 0x4000000
	v_writelane_b32 v254, s0, 37
	s_addc_u32 s87, s21, 0
	s_cmpk_lg_i32 s84, 0x100
	v_writelane_b32 v254, s1, 38
	s_cselect_b64 s[96:97], -1, 0
	s_and_b32 s0, s2, 7
	v_writelane_b32 v254, s2, 39
	s_ashr_i32 s1, s2, 3
	v_writelane_b32 v254, s1, 40
	s_xor_b32 s1, s0, 15
	v_writelane_b32 v254, s1, 41
	s_or_b32 s1, s0, 16
	v_writelane_b32 v254, s1, 42
	v_writelane_b32 v254, s0, 43
	s_xor_b32 s0, s0, 31
	v_writelane_b32 v254, s0, 44
	v_writelane_b32 v254, s16, 45
	s_mov_b64 s[8:9], 0x20000
	s_mov_b64 s[10:11], 0x40000
	s_mov_b64 s[12:13], 0x60000
	s_mov_b64 s[14:15], 0x80000
	s_mov_b64 s[42:43], 0x13040000
	s_mov_b64 s[48:49], 0x13040080
	s_mov_b32 s25, 0x41000000
	v_mov_b32_e32 v230, 0x3727c5ac
	v_mov_b32_e32 v231, 0xff800000
	s_mov_b32 s27, 0
	v_writelane_b32 v254, s40, 46
	s_waitcnt vmcnt(2)
	v_mul_f32_e32 v7, v2, v3
	ds_bpermute_b32 v7, v232, v7
	s_waitcnt vmcnt(0)
	v_mul_f32_e32 v13, v4, v0
	ds_bpermute_b32 v13, v232, v13
	v_writelane_b32 v254, s41, 47
	s_waitcnt lgkmcnt(1)
	v_fmac_f32_e32 v7, v2, v3
	v_cndmask_b32_e32 v3, v5, v11, vcc
	s_waitcnt lgkmcnt(0)
	v_fmac_f32_e32 v13, v4, v0
	ds_bpermute_b32 v0, v8, v7
	ds_bpermute_b32 v2, v8, v13
	v_lshlrev_b32_e32 v4, 2, v9
	v_cmp_lt_i32_e32 vcc, v12, v6
	v_lshlrev_b32_e32 v6, 2, v10
	s_waitcnt lgkmcnt(1)
	v_add_f32_e32 v0, v7, v0
	s_waitcnt lgkmcnt(0)
	v_add_f32_e32 v2, v13, v2
	ds_bpermute_b32 v7, v4, v0
	ds_bpermute_b32 v4, v4, v2
	v_lshlrev_b32_e32 v245, 2, v3
	v_cndmask_b32_e32 v5, v5, v12, vcc
	v_lshlrev_b32_e32 v246, 2, v5
	s_waitcnt lgkmcnt(1)
	v_add_f32_e32 v0, v0, v7
	s_waitcnt lgkmcnt(0)
	v_add_f32_e32 v2, v2, v4
	ds_bpermute_b32 v4, v6, v0
	ds_bpermute_b32 v6, v6, v2
	s_waitcnt lgkmcnt(1)
	v_add_f32_e32 v0, v0, v4
	s_waitcnt lgkmcnt(0)
	v_add_f32_e32 v2, v2, v6
	ds_bpermute_b32 v3, v245, v0
	ds_bpermute_b32 v4, v245, v2
	s_waitcnt lgkmcnt(1)
	v_add_f32_e32 v0, v0, v3
	s_waitcnt lgkmcnt(0)
	v_add_f32_e32 v2, v2, v4
	ds_bpermute_b32 v3, v246, v0
	ds_bpermute_b32 v4, v246, v2
	s_waitcnt lgkmcnt(1)
	v_add_f32_e32 v0, v0, v3
	s_waitcnt lgkmcnt(0)
	v_add_f32_e32 v2, v2, v4
	v_mul_f32_e32 v0, 0x3fb8aa3b, v0
	v_mul_f32_e32 v2, 0x3fb8aa3b, v2
	v_exp_f32_e32 v0, v0
	v_exp_f32_e32 v2, v2
	s_nop 0
	v_sub_f32_e32 v0, v0, v2
	v_add_f32_e32 v233, 0x3e4ccccd, v0
	s_mov_b32 s100, 0
	s_branch .LBB0_281

.LBB0_296:
	v_mov_b32_e32 v234, v244
	s_or_b32 s6, s0, s31
	v_readfirstlane_b32 s51, v234
	s_ashr_i32 s44, s51, 6
	s_lshl_b32 s38, s44, 5
	s_ashr_i32 s0, s38, 31
	s_add_u32 s74, s35, s38
	s_addc_u32 s75, s84, s0
	s_lshl_b64 s[0:1], s[74:75], 11
	s_add_u32 s2, s94, s0
	s_addc_u32 s3, s95, s1
	s_lshl_b64 s[0:1], s[6:7], 1
	s_add_u32 s2, s2, s0
	s_addc_u32 s3, s3, s1
	v_and_b32_e32 v235, 63, v234
	s_add_u32 s0, s87, s0
	s_addc_u32 s1, s96, s1
	v_lshlrev_b32_e32 v0, 11, v235
	v_lshl_add_u64 v[2:3], s[0:1], 0, v[0:1]
	s_lshl_b32 s0, s44, 3
	s_ashr_i32 s1, s0, 31
	v_lshl_add_u64 v[224:225], s[0:1], 1, v[2:3]
	s_lshl_b32 s0, s44, 4
	v_bfe_u32 v251, v234, 2, 4
	v_and_or_b32 v0, s0, 48, v251
	s_ashr_i32 s0, s51, 3
	s_and_b32 s76, s0, 0xffffffe0
	v_lshlrev_b32_e32 v0, 11, v0
	s_ashr_i32 s77, s76, 31
	s_lshl_b32 s0, s44, 10
	v_lshl_add_u64 v[2:3], s[62:63], 0, v[0:1]
	v_lshlrev_b32_e32 v0, 3, v234
	s_cmp_lg_u32 0, -1
	v_and_b32_e32 v238, 24, v0
	s_cselect_b32 s1, 0, 0
	v_lshl_add_u64 v[2:3], s[76:77], 1, v[2:3]
	v_lshlrev_b32_e32 v0, 1, v238
	s_add_i32 s46, s0, s1
	s_cmp_lg_u32 s100, 0
	s_cbranch_scc1 .Lkp_skip0
	s_mov_b32 s1, m0
	s_mov_b32 m0, s46
	s_nop 0
	global_load_lds_dwordx4 v[224:225], off
	s_mov_b32 m0, s1
.Lkp_skip0:
	v_and_b32_e32 v236, 31, v234
	v_lshl_add_u64 v[34:35], v[2:3], 0, v[0:1]
	s_add_i32 s47, s46, 0x6000
	s_mov_b32 s1, m0
	s_mov_b32 m0, s47
	s_nop 0
	global_load_lds_dwordx4 v[34:35], off
	s_mov_b32 m0, s1
	s_mov_b64 s[18:19], 0x80
	v_bfe_u32 v252, v234, 5, 1
	v_lshl_add_u64 v[2:3], v[34:35], 0, s[18:19]
	s_add_i32 s1, s46, 0x8000
	s_mov_b32 s6, m0
	s_mov_b32 m0, s1
	s_nop 0
	global_load_lds_dwordx4 v[2:3], off
	s_mov_b32 m0, s6
	v_lshlrev_b32_e32 v0, 11, v236
	v_lshl_add_u64 v[2:3], v[224:225], 0, s[8:9]
	s_add_i32 s1, s46, 0x2000
	s_cmp_lg_u32 s100, 0
	s_cbranch_scc1 .Lkp_skip1
	s_mov_b32 s6, m0
	s_mov_b32 m0, s1
	s_nop 0
	global_load_lds_dwordx4 v[2:3], off
	s_mov_b32 m0, s6
.Lkp_skip1:
	v_lshl_or_b32 v0, v252, 4, v0
	global_load_dwordx4 v[188:191], v0, s[2:3]
	global_load_dwordx4 v[184:187], v0, s[2:3] offset:32
	global_load_dwordx4 v[176:179], v0, s[2:3] offset:64
	global_load_dwordx4 v[168:171], v0, s[2:3] offset:96
	v_mov_b32_e32 v2, v1
	v_mov_b32_e32 v3, v1
	v_mov_b32_e32 v4, v1
	v_mov_b32_e32 v5, v1
	v_mov_b32_e32 v6, v1
	v_mov_b32_e32 v7, v1
	v_mov_b32_e32 v8, v1
	v_mov_b32_e32 v9, v1
	v_mov_b32_e32 v10, v1
	v_mov_b32_e32 v11, v1
	v_mov_b32_e32 v12, v1
	v_mov_b32_e32 v13, v1
	v_mov_b32_e32 v14, v1
	v_mov_b32_e32 v15, v1
	v_lshlrev_b32_e32 v0, 10, v252
	v_lshlrev_b32_e32 v16, 4, v236
	v_add3_u32 v247, 0, v0, v16
	v_mov_b32_e32 v0, v1
	v_mov_b64_e32 v[16:17], v[14:15]
	v_mov_b64_e32 v[14:15], v[12:13]
	v_mov_b64_e32 v[12:13], v[10:11]
	v_mov_b64_e32 v[10:11], v[8:9]
	v_mov_b64_e32 v[8:9], v[6:7]
	v_mov_b64_e32 v[6:7], v[4:5]
	v_mov_b64_e32 v[4:5], v[2:3]
	v_mov_b64_e32 v[2:3], v[0:1]
	v_lshl_add_u64 v[18:19], v[224:225], 0, s[10:11]
	s_add_i32 s1, s46, 0x4000
	s_cmp_lg_u32 s100, 0
	s_cbranch_scc1 .Lkp_skip2
	s_mov_b32 s2, m0
	s_mov_b32 m0, s1
	s_nop 0
	global_load_lds_dwordx4 v[18:19], off
	s_mov_b32 m0, s2
.Lkp_skip2:
	s_waitcnt vmcnt(3) lgkmcnt(0)
	s_barrier
	ds_read_b128 v[36:39], v247
	v_or_b32_e32 v242, s38, v236
	s_andn2_b64 vcc, exec, s[54:55]
	v_lshlrev_b32_e32 v237, 2, v252
	s_waitcnt vmcnt(3) lgkmcnt(0)
	v_mfma_f32_32x32x16_bf16 v[18:33], v[36:39], v[188:191], v[2:17]
	ds_read_b128 v[36:39], v247 offset:512
	s_waitcnt lgkmcnt(0)
	v_mfma_f32_32x32x16_bf16 v[2:17], v[36:39], v[188:191], v[2:17]
	ds_read_b128 v[36:39], v247 offset:2048
	s_waitcnt vmcnt(2) lgkmcnt(0)
	v_mfma_f32_32x32x16_bf16 v[18:33], v[36:39], v[184:187], v[18:33]
	ds_read_b128 v[36:39], v247 offset:2560
	s_waitcnt lgkmcnt(0)
	v_mfma_f32_32x32x16_bf16 v[2:17], v[36:39], v[184:187], v[2:17]
	ds_read_b128 v[36:39], v247 offset:4096
	s_waitcnt vmcnt(1) lgkmcnt(0)
	v_mfma_f32_32x32x16_bf16 v[18:33], v[36:39], v[176:179], v[18:33]
	ds_read_b128 v[36:39], v247 offset:4608
	s_waitcnt lgkmcnt(0)
	v_mfma_f32_32x32x16_bf16 v[2:17], v[36:39], v[176:179], v[2:17]
	ds_read_b128 v[36:39], v247 offset:6144
	s_waitcnt vmcnt(0) lgkmcnt(0)
	v_mfma_f32_32x32x16_bf16 v[18:33], v[36:39], v[168:171], v[18:33]
	ds_read_b128 v[36:39], v247 offset:6656
	s_waitcnt lgkmcnt(0)
	v_mfma_f32_32x32x16_bf16 v[2:17], v[36:39], v[168:171], v[2:17]
	s_nop 15
	s_nop 7
	s_cbranch_vccnz .LBB0_298
	v_lshlrev_b32_e32 v0, 2, v252
	v_subrev_u32_e32 v0, s34, v0
	v_or_b32_e32 v36, 32, v0
	v_cmp_le_i32_e32 vcc, v36, v242
	v_or_b32_e32 v36, 33, v0
	s_nop 5
	v_cndmask_b32_e32 v2, v231, v2, vcc
	v_cmp_lt_i32_e32 vcc, v0, v242
	s_nop 1
	v_cndmask_b32_e32 v19, v231, v19, vcc
	v_cmp_le_i32_e32 vcc, v0, v242
	s_nop 1
	v_cndmask_b32_e32 v18, v231, v18, vcc
	v_cmp_le_i32_e32 vcc, v36, v242
	v_or_b32_e32 v36, 2, v0
	s_nop 0
	v_cndmask_b32_e32 v3, v231, v3, vcc
	v_cmp_le_i32_e32 vcc, v36, v242
	v_or_b32_e32 v36, 34, v0
	s_nop 0
	v_cndmask_b32_e32 v20, v231, v20, vcc
	v_cmp_le_i32_e32 vcc, v36, v242
	v_or_b32_e32 v36, 3, v0
	s_nop 0
	v_cndmask_b32_e32 v4, v231, v4, vcc
	v_cmp_le_i32_e32 vcc, v36, v242
	v_or_b32_e32 v36, 35, v0
	s_nop 0
	v_cndmask_b32_e32 v21, v231, v21, vcc
	v_cmp_le_i32_e32 vcc, v36, v242
	v_or_b32_e32 v36, 8, v0
	s_nop 0
	v_cndmask_b32_e32 v5, v231, v5, vcc
	v_cmp_le_i32_e32 vcc, v36, v242
	v_or_b32_e32 v36, 40, v0
	s_nop 0
	v_cndmask_b32_e32 v22, v231, v22, vcc
	v_cmp_le_i32_e32 vcc, v36, v242
	v_or_b32_e32 v36, 9, v0
	s_nop 0
	v_cndmask_b32_e32 v6, v231, v6, vcc
	v_cmp_le_i32_e32 vcc, v36, v242
	v_or_b32_e32 v36, 41, v0
	s_nop 0
	v_cndmask_b32_e32 v23, v231, v23, vcc
	v_cmp_le_i32_e32 vcc, v36, v242
	v_or_b32_e32 v36, 10, v0
	s_nop 0
	v_cndmask_b32_e32 v7, v231, v7, vcc
	v_cmp_le_i32_e32 vcc, v36, v242
	v_or_b32_e32 v36, 42, v0
	s_nop 0
	v_cndmask_b32_e32 v24, v231, v24, vcc
	v_cmp_le_i32_e32 vcc, v36, v242
	v_or_b32_e32 v36, 11, v0
	s_nop 0
	v_cndmask_b32_e32 v8, v231, v8, vcc
	v_cmp_le_i32_e32 vcc, v36, v242
	v_or_b32_e32 v36, 43, v0
	s_nop 0
	v_cndmask_b32_e32 v25, v231, v25, vcc
	v_cmp_le_i32_e32 vcc, v36, v242
	v_or_b32_e32 v36, 16, v0
	s_nop 0
	v_cndmask_b32_e32 v9, v231, v9, vcc
	v_cmp_le_i32_e32 vcc, v36, v242
	v_or_b32_e32 v36, 48, v0
	s_nop 0
	v_cndmask_b32_e32 v26, v231, v26, vcc
	v_cmp_le_i32_e32 vcc, v36, v242
	v_or_b32_e32 v36, 17, v0
	s_nop 0
	v_cndmask_b32_e32 v10, v231, v10, vcc
	v_cmp_le_i32_e32 vcc, v36, v242
	v_or_b32_e32 v36, 49, v0
	s_nop 0
	v_cndmask_b32_e32 v27, v231, v27, vcc
	v_cmp_le_i32_e32 vcc, v36, v242
	v_or_b32_e32 v36, 18, v0
	s_nop 0
	v_cndmask_b32_e32 v11, v231, v11, vcc
	v_cmp_le_i32_e32 vcc, v36, v242
	v_or_b32_e32 v36, 50, v0
	s_nop 0
	v_cndmask_b32_e32 v28, v231, v28, vcc
	v_cmp_le_i32_e32 vcc, v36, v242
	v_or_b32_e32 v36, 19, v0
	s_nop 0
	v_cndmask_b32_e32 v12, v231, v12, vcc
	v_cmp_le_i32_e32 vcc, v36, v242
	v_or_b32_e32 v36, 51, v0
	s_nop 0
	v_cndmask_b32_e32 v29, v231, v29, vcc
	v_cmp_le_i32_e32 vcc, v36, v242
	v_or_b32_e32 v36, 24, v0
	s_nop 0
	v_cndmask_b32_e32 v13, v231, v13, vcc
	v_cmp_le_i32_e32 vcc, v36, v242
	v_or_b32_e32 v36, 56, v0
	s_nop 0
	v_cndmask_b32_e32 v30, v231, v30, vcc
	v_cmp_le_i32_e32 vcc, v36, v242
	v_or_b32_e32 v36, 25, v0
	s_nop 0
	v_cndmask_b32_e32 v14, v231, v14, vcc
	v_cmp_le_i32_e32 vcc, v36, v242
	v_or_b32_e32 v36, 57, v0
	s_nop 0
	v_cndmask_b32_e32 v31, v231, v31, vcc
	v_cmp_le_i32_e32 vcc, v36, v242
	v_or_b32_e32 v36, 26, v0
	s_nop 0
	v_cndmask_b32_e32 v15, v231, v15, vcc
	v_cmp_le_i32_e32 vcc, v36, v242
	v_or_b32_e32 v36, 58, v0
	s_nop 0
	v_cndmask_b32_e32 v32, v231, v32, vcc
	v_cmp_le_i32_e32 vcc, v36, v242
	v_or_b32_e32 v36, 27, v0
	v_or_b32_e32 v0, 59, v0
	v_cndmask_b32_e32 v16, v231, v16, vcc
	v_cmp_le_i32_e32 vcc, v36, v242
	s_nop 1
	v_cndmask_b32_e32 v33, v231, v33, vcc
	v_cmp_le_i32_e32 vcc, v0, v242
	s_nop 1
	v_cndmask_b32_e32 v17, v231, v17, vcc

.LBB0_319:
	s_mov_b32 s100, 0
	s_cmp_lg_u64 s[72:73], 0
	s_cbranch_scc0 .Lkp_go
	s_cmp_eq_u32 s27, 3
	s_cbranch_scc1 .Lkp_done
.Lkp_go:
	s_mov_b32 s100, 1
	s_lshl_b32 s98, s31, 1
	s_add_u32 s98, s87, s98
	s_addc_u32 s99, s96, 0
	s_cmp_lg_u64 s[72:73], 0
	s_cbranch_scc1 .Lkp_m1
	s_add_u32 s98, s98, 0x80
	s_addc_u32 s99, s99, 0
.Lkp_m1:
	v_and_b32_e32 v253, 63, v244
	v_lshlrev_b32_e32 v253, 11, v253
	v_lshrrev_b32_e32 v255, 6, v244
	v_lshl_add_u32 v253, v255, 4, v253
	s_mov_b32 s101, m0
	s_mov_b32 m0, s46
	s_nop 0
	global_load_lds_dwordx4 v253, s[98:99]
	s_add_u32 s98, s98, 0x20000
	s_addc_u32 s99, s99, 0
	s_add_i32 m0, s46, 0x2000
	s_nop 0
	global_load_lds_dwordx4 v253, s[98:99]
	s_add_u32 s98, s98, 0x20000
	s_addc_u32 s99, s99, 0
	s_add_i32 m0, s46, 0x4000
	s_nop 0
	global_load_lds_dwordx4 v253, s[98:99]
	s_mov_b32 m0, s101
